# v097 plus: GEMM K loops without per-cluster s_setprio toggling, one static priority raise for waves 4-7 in the K loops; attention placement kept modulo 64 bytes
# baseline (speedup 1.0000x reference)
.Lprio_189:
	s_add_u32 s1, s68, 0xfff80080
	s_addc_u32 s2, s69, -1
	s_add_i32 s3, 0, 0x10000
	v_add_u32_e32 v154, s3, v143
	ds_read_b128 v[138:141], v154
	ds_read_b128 v[146:149], v154 offset:1024
	ds_read_b128 v[150:153], v154 offset:2048
	ds_read_b128 v[154:157], v154 offset:3072
	s_cmp_eq_u32 s87, 28
	s_cselect_b32 s73, s43, s2
	s_cselect_b32 s72, s81, s1
	s_cselect_b32 s71, s41, s86
	s_cselect_b32 s70, s82, s83
	v_lshl_add_u64 v[174:175], s[68:69], 0, v[134:135]
	s_add_i32 m0, s60, 0xc000
	ds_read_b128 v[158:161], v145
	ds_read_b128 v[162:165], v145 offset:1024
	ds_read_b128 v[166:169], v145 offset:2048
	ds_read_b128 v[170:173], v145 offset:3072
	ds_read_b128 v[182:185], v145 offset:4096
	ds_read_b128 v[206:209], v145 offset:5120
	ds_read_b128 v[210:213], v145 offset:6144
	ds_read_b128 v[214:217], v145 offset:7168
	global_load_lds_dwordx4 v[174:175], off
	v_lshl_add_u64 v[174:175], s[68:69], 0, v[136:137]
	s_add_i32 m0, s60, 0xe000
	s_nop 0
	global_load_lds_dwordx4 v[174:175], off
	s_waitcnt lgkmcnt(8)
	s_barrier
	s_waitcnt lgkmcnt(0)
	s_waitcnt lgkmcnt(0)
	v_mfma_f32_16x16x32_bf16 v[124:127], v[138:141], v[158:161], v[124:127]
	v_mfma_f32_16x16x32_bf16 v[120:123], v[150:153], v[158:161], v[120:123]
	v_mfma_f32_16x16x32_bf16 v[116:119], v[138:141], v[166:169], v[116:119]
	v_mfma_f32_16x16x32_bf16 v[108:111], v[150:153], v[166:169], v[108:111]
	v_mfma_f32_16x16x32_bf16 v[100:103], v[138:141], v[182:185], v[100:103]
	v_mfma_f32_16x16x32_bf16 v[92:95], v[150:153], v[182:185], v[92:95]
	v_mfma_f32_16x16x32_bf16 v[84:87], v[138:141], v[210:213], v[84:87]
	v_mfma_f32_16x16x32_bf16 v[76:79], v[150:153], v[210:213], v[76:79]
	v_mfma_f32_16x16x32_bf16 v[124:127], v[146:149], v[162:165], v[124:127]
	v_mfma_f32_16x16x32_bf16 v[120:123], v[154:157], v[162:165], v[120:123]
	v_mfma_f32_16x16x32_bf16 v[116:119], v[146:149], v[170:173], v[116:119]
	v_mfma_f32_16x16x32_bf16 v[108:111], v[154:157], v[170:173], v[108:111]
	v_mfma_f32_16x16x32_bf16 v[100:103], v[146:149], v[206:209], v[100:103]
	v_mfma_f32_16x16x32_bf16 v[92:95], v[154:157], v[206:209], v[92:95]
	v_mfma_f32_16x16x32_bf16 v[84:87], v[146:149], v[214:217], v[84:87]
	v_mfma_f32_16x16x32_bf16 v[76:79], v[154:157], v[214:217], v[76:79]
	s_barrier
	s_add_i32 s1, 0, 0x14000
	v_add_u32_e32 v174, s1, v143
	s_add_i32 s2, s3, s53
	ds_read_b128 v[218:221], v174
	ds_read_b128 v[222:225], v174 offset:1024
	ds_read_b128 v[226:229], v174 offset:2048
	ds_read_b128 v[230:233], v174 offset:3072
	v_lshl_add_u64 v[174:175], s[70:71], 0, v[176:177]
	s_mov_b32 m0, s2
	v_lshl_add_u64 v[186:187], s[70:71], 0, v[128:129]
	global_load_lds_dwordx4 v[174:175], off
	s_add_i32 m0, s2, 0x2000
	s_nop 0
	global_load_lds_dwordx4 v[186:187], off
	s_barrier
	s_waitcnt lgkmcnt(0)
	s_waitcnt lgkmcnt(0)
	v_mfma_f32_16x16x32_bf16 v[112:115], v[218:221], v[158:161], v[112:115]
	v_mfma_f32_16x16x32_bf16 v[104:107], v[226:229], v[158:161], v[104:107]
	v_mfma_f32_16x16x32_bf16 v[96:99], v[218:221], v[166:169], v[96:99]
	v_mfma_f32_16x16x32_bf16 v[88:91], v[226:229], v[166:169], v[88:91]
	v_mfma_f32_16x16x32_bf16 v[80:83], v[218:221], v[182:185], v[80:83]
	v_mfma_f32_16x16x32_bf16 v[72:75], v[226:229], v[182:185], v[72:75]
	v_mfma_f32_16x16x32_bf16 v[68:71], v[218:221], v[210:213], v[68:71]
	v_mfma_f32_16x16x32_bf16 v[64:67], v[226:229], v[210:213], v[64:67]
	v_mfma_f32_16x16x32_bf16 v[112:115], v[222:225], v[162:165], v[112:115]
	v_mfma_f32_16x16x32_bf16 v[104:107], v[230:233], v[162:165], v[104:107]
	v_mfma_f32_16x16x32_bf16 v[96:99], v[222:225], v[170:173], v[96:99]
	v_mfma_f32_16x16x32_bf16 v[88:91], v[230:233], v[170:173], v[88:91]
	v_mfma_f32_16x16x32_bf16 v[80:83], v[222:225], v[206:209], v[80:83]
	v_mfma_f32_16x16x32_bf16 v[72:75], v[230:233], v[206:209], v[72:75]
	v_mfma_f32_16x16x32_bf16 v[68:71], v[222:225], v[214:217], v[68:71]
	v_mfma_f32_16x16x32_bf16 v[64:67], v[230:233], v[214:217], v[64:67]
	s_mov_b32 m0, s60
	v_lshl_add_u64 v[200:201], s[72:73], 0, v[132:133]
	s_barrier
	ds_read_b128 v[158:161], v145 offset:16384
	ds_read_b128 v[162:165], v145 offset:17408
	ds_read_b128 v[166:169], v145 offset:18432
	ds_read_b128 v[170:173], v145 offset:19456
	ds_read_b128 v[182:185], v145 offset:20480
	ds_read_b128 v[206:209], v145 offset:21504
	ds_read_b128 v[210:213], v145 offset:22528
	ds_read_b128 v[214:217], v145 offset:23552
	global_load_lds_dwordx4 v[200:201], off
	v_lshl_add_u64 v[202:203], s[72:73], 0, v[130:131]
	s_mov_b32 m0, s61
	s_nop 0
	global_load_lds_dwordx4 v[202:203], off
	s_barrier
	s_waitcnt lgkmcnt(0)
	s_waitcnt lgkmcnt(0)
	v_mfma_f32_16x16x32_bf16 v[60:63], v[138:141], v[158:161], v[60:63]
	v_mfma_f32_16x16x32_bf16 v[56:59], v[150:153], v[158:161], v[56:59]
	v_mfma_f32_16x16x32_bf16 v[52:55], v[138:141], v[166:169], v[52:55]
	v_mfma_f32_16x16x32_bf16 v[44:47], v[150:153], v[166:169], v[44:47]
	v_mfma_f32_16x16x32_bf16 v[36:39], v[138:141], v[182:185], v[36:39]
	v_mfma_f32_16x16x32_bf16 v[28:31], v[150:153], v[182:185], v[28:31]
	v_mfma_f32_16x16x32_bf16 v[20:23], v[138:141], v[210:213], v[20:23]
	v_mfma_f32_16x16x32_bf16 v[12:15], v[150:153], v[210:213], v[12:15]
	v_mfma_f32_16x16x32_bf16 v[60:63], v[146:149], v[162:165], v[60:63]
	v_mfma_f32_16x16x32_bf16 v[56:59], v[154:157], v[162:165], v[56:59]
	v_mfma_f32_16x16x32_bf16 v[52:55], v[146:149], v[170:173], v[52:55]
	v_mfma_f32_16x16x32_bf16 v[44:47], v[154:157], v[170:173], v[44:47]
	v_mfma_f32_16x16x32_bf16 v[36:39], v[146:149], v[206:209], v[36:39]
	v_mfma_f32_16x16x32_bf16 v[28:31], v[154:157], v[206:209], v[28:31]
	v_mfma_f32_16x16x32_bf16 v[20:23], v[146:149], v[214:217], v[20:23]
	v_mfma_f32_16x16x32_bf16 v[12:15], v[154:157], v[214:217], v[12:15]
	s_barrier
	s_add_u32 s2, s70, 0x80000
	s_addc_u32 s3, s71, 0
	s_add_i32 s1, s1, s53
	v_lshl_add_u64 v[138:139], s[2:3], 0, v[176:177]
	s_mov_b32 m0, s1
	s_nop 0
	global_load_lds_dwordx4 v[138:139], off
	v_lshl_add_u64 v[138:139], s[2:3], 0, v[128:129]
	s_add_i32 m0, s1, 0x2000
	s_nop 0
	global_load_lds_dwordx4 v[138:139], off
	s_waitcnt vmcnt(6)
	s_barrier
	v_mfma_f32_16x16x32_bf16 v[48:51], v[218:221], v[158:161], v[48:51]
	v_mfma_f32_16x16x32_bf16 v[40:43], v[226:229], v[158:161], v[40:43]
	v_mfma_f32_16x16x32_bf16 v[32:35], v[218:221], v[166:169], v[32:35]
	v_mfma_f32_16x16x32_bf16 v[24:27], v[226:229], v[166:169], v[24:27]
	v_mfma_f32_16x16x32_bf16 v[16:19], v[218:221], v[182:185], v[16:19]
	v_mfma_f32_16x16x32_bf16 v[8:11], v[226:229], v[182:185], v[8:11]
	v_mfma_f32_16x16x32_bf16 v[4:7], v[218:221], v[210:213], v[4:7]
	v_mfma_f32_16x16x32_bf16 v[0:3], v[226:229], v[210:213], v[0:3]
	v_mfma_f32_16x16x32_bf16 v[48:51], v[222:225], v[162:165], v[48:51]
	v_mfma_f32_16x16x32_bf16 v[40:43], v[230:233], v[162:165], v[40:43]
	v_mfma_f32_16x16x32_bf16 v[32:35], v[222:225], v[170:173], v[32:35]
	v_mfma_f32_16x16x32_bf16 v[24:27], v[230:233], v[170:173], v[24:27]
	v_mfma_f32_16x16x32_bf16 v[16:19], v[222:225], v[206:209], v[16:19]
	v_mfma_f32_16x16x32_bf16 v[8:11], v[230:233], v[206:209], v[8:11]
	v_mfma_f32_16x16x32_bf16 v[4:7], v[222:225], v[214:217], v[4:7]
	v_mfma_f32_16x16x32_bf16 v[0:3], v[230:233], v[214:217], v[0:3]
	s_add_i32 s1, 0, 0x18000
	v_add_u32_e32 v154, s1, v143
	s_barrier
	ds_read_b128 v[138:141], v154
	ds_read_b128 v[146:149], v154 offset:1024
	ds_read_b128 v[150:153], v154 offset:2048
	ds_read_b128 v[154:157], v154 offset:3072
	s_add_u32 s2, s72, 0x80000
	s_addc_u32 s3, s73, 0
	s_mov_b32 m0, s74
	v_lshl_add_u64 v[204:205], s[2:3], 0, v[132:133]
	ds_read_b128 v[158:161], v145 offset:32768
	ds_read_b128 v[162:165], v145 offset:33792
	ds_read_b128 v[166:169], v145 offset:34816
	ds_read_b128 v[170:173], v145 offset:35840
	ds_read_b128 v[182:185], v145 offset:36864
	ds_read_b128 v[206:209], v145 offset:37888
	ds_read_b128 v[210:213], v145 offset:38912
	ds_read_b128 v[214:217], v145 offset:39936
	global_load_lds_dwordx4 v[204:205], off
	v_lshl_add_u64 v[204:205], s[2:3], 0, v[130:131]
	s_mov_b32 m0, s75
	s_nop 0
	global_load_lds_dwordx4 v[204:205], off
	s_waitcnt lgkmcnt(8)
	s_barrier
	s_waitcnt lgkmcnt(0)
	s_waitcnt lgkmcnt(0)
	v_mfma_f32_16x16x32_bf16 v[124:127], v[138:141], v[158:161], v[124:127]
	v_mfma_f32_16x16x32_bf16 v[120:123], v[150:153], v[158:161], v[120:123]
	v_mfma_f32_16x16x32_bf16 v[116:119], v[138:141], v[166:169], v[116:119]
	v_mfma_f32_16x16x32_bf16 v[108:111], v[150:153], v[166:169], v[108:111]
	v_mfma_f32_16x16x32_bf16 v[100:103], v[138:141], v[182:185], v[100:103]
	v_mfma_f32_16x16x32_bf16 v[92:95], v[150:153], v[182:185], v[92:95]
	v_mfma_f32_16x16x32_bf16 v[84:87], v[138:141], v[210:213], v[84:87]
	v_mfma_f32_16x16x32_bf16 v[76:79], v[150:153], v[210:213], v[76:79]
	v_mfma_f32_16x16x32_bf16 v[124:127], v[146:149], v[162:165], v[124:127]
	v_mfma_f32_16x16x32_bf16 v[120:123], v[154:157], v[162:165], v[120:123]
	v_mfma_f32_16x16x32_bf16 v[116:119], v[146:149], v[170:173], v[116:119]
	v_mfma_f32_16x16x32_bf16 v[108:111], v[154:157], v[170:173], v[108:111]
	v_mfma_f32_16x16x32_bf16 v[100:103], v[146:149], v[206:209], v[100:103]
	v_mfma_f32_16x16x32_bf16 v[92:95], v[154:157], v[206:209], v[92:95]
	v_mfma_f32_16x16x32_bf16 v[84:87], v[146:149], v[214:217], v[84:87]
	v_mfma_f32_16x16x32_bf16 v[76:79], v[154:157], v[214:217], v[76:79]
	s_barrier
	s_add_i32 s12, 0, 0x1c000
	s_add_i32 s1, s1, s53
	v_add_u32_e32 v188, s12, v143
	v_lshl_add_u64 v[174:175], v[174:175], 0, s[20:21]
	s_mov_b32 m0, s1
	ds_read_b128 v[218:221], v188
	ds_read_b128 v[222:225], v188 offset:1024
	ds_read_b128 v[226:229], v188 offset:2048
	ds_read_b128 v[230:233], v188 offset:3072
	global_load_lds_dwordx4 v[174:175], off
	v_lshl_add_u64 v[174:175], v[186:187], 0, s[20:21]
	s_add_i32 m0, s1, 0x2000
	s_nop 0
	global_load_lds_dwordx4 v[174:175], off
	s_barrier
	s_waitcnt lgkmcnt(0)
	s_waitcnt lgkmcnt(0)
	v_mfma_f32_16x16x32_bf16 v[112:115], v[218:221], v[158:161], v[112:115]
	v_mfma_f32_16x16x32_bf16 v[104:107], v[226:229], v[158:161], v[104:107]
	v_mfma_f32_16x16x32_bf16 v[96:99], v[218:221], v[166:169], v[96:99]
	v_mfma_f32_16x16x32_bf16 v[88:91], v[226:229], v[166:169], v[88:91]
	v_mfma_f32_16x16x32_bf16 v[80:83], v[218:221], v[182:185], v[80:83]
	v_mfma_f32_16x16x32_bf16 v[72:75], v[226:229], v[182:185], v[72:75]
	v_mfma_f32_16x16x32_bf16 v[68:71], v[218:221], v[210:213], v[68:71]
	v_mfma_f32_16x16x32_bf16 v[64:67], v[226:229], v[210:213], v[64:67]
	v_mfma_f32_16x16x32_bf16 v[112:115], v[222:225], v[162:165], v[112:115]
	v_mfma_f32_16x16x32_bf16 v[104:107], v[230:233], v[162:165], v[104:107]
	v_mfma_f32_16x16x32_bf16 v[96:99], v[222:225], v[170:173], v[96:99]
	v_mfma_f32_16x16x32_bf16 v[88:91], v[230:233], v[170:173], v[88:91]
	v_mfma_f32_16x16x32_bf16 v[80:83], v[222:225], v[206:209], v[80:83]
	v_mfma_f32_16x16x32_bf16 v[72:75], v[230:233], v[206:209], v[72:75]
	v_mfma_f32_16x16x32_bf16 v[68:71], v[222:225], v[214:217], v[68:71]
	v_mfma_f32_16x16x32_bf16 v[64:67], v[230:233], v[214:217], v[64:67]
	s_mov_b32 m0, s76
	v_lshl_add_u64 v[174:175], v[200:201], 0, s[20:21]
	s_barrier
	ds_read_b128 v[158:161], v145 offset:49152
	ds_read_b128 v[162:165], v145 offset:50176
	ds_read_b128 v[166:169], v145 offset:51200
	ds_read_b128 v[170:173], v145 offset:52224
	ds_read_b128 v[182:185], v145 offset:53248
	ds_read_b128 v[206:209], v145 offset:54272
	ds_read_b128 v[210:213], v145 offset:55296
	ds_read_b128 v[214:217], v145 offset:56320
	global_load_lds_dwordx4 v[174:175], off
	v_lshl_add_u64 v[174:175], v[202:203], 0, s[20:21]
	s_mov_b32 m0, s77
	s_nop 0
	global_load_lds_dwordx4 v[174:175], off
	s_barrier
	s_waitcnt lgkmcnt(0)
	s_waitcnt lgkmcnt(0)
	v_mfma_f32_16x16x32_bf16 v[60:63], v[138:141], v[158:161], v[60:63]
	v_mfma_f32_16x16x32_bf16 v[56:59], v[150:153], v[158:161], v[56:59]
	v_mfma_f32_16x16x32_bf16 v[52:55], v[138:141], v[166:169], v[52:55]
	v_mfma_f32_16x16x32_bf16 v[44:47], v[150:153], v[166:169], v[44:47]
	v_mfma_f32_16x16x32_bf16 v[36:39], v[138:141], v[182:185], v[36:39]
	v_mfma_f32_16x16x32_bf16 v[28:31], v[150:153], v[182:185], v[28:31]
	v_mfma_f32_16x16x32_bf16 v[20:23], v[138:141], v[210:213], v[20:23]
	v_mfma_f32_16x16x32_bf16 v[12:15], v[150:153], v[210:213], v[12:15]
	v_mfma_f32_16x16x32_bf16 v[60:63], v[146:149], v[162:165], v[60:63]
	v_mfma_f32_16x16x32_bf16 v[56:59], v[154:157], v[162:165], v[56:59]
	v_mfma_f32_16x16x32_bf16 v[52:55], v[146:149], v[170:173], v[52:55]
	v_mfma_f32_16x16x32_bf16 v[44:47], v[154:157], v[170:173], v[44:47]
	v_mfma_f32_16x16x32_bf16 v[36:39], v[146:149], v[206:209], v[36:39]
	v_mfma_f32_16x16x32_bf16 v[28:31], v[154:157], v[206:209], v[28:31]
	v_mfma_f32_16x16x32_bf16 v[20:23], v[146:149], v[214:217], v[20:23]
	v_mfma_f32_16x16x32_bf16 v[12:15], v[154:157], v[214:217], v[12:15]
	s_barrier
	s_add_u32 s2, s70, 0x80080
	s_addc_u32 s3, s71, 0
	s_add_i32 s1, s12, s53
	v_lshl_add_u64 v[138:139], s[2:3], 0, v[176:177]
	s_mov_b32 m0, s1
	s_nop 0
	global_load_lds_dwordx4 v[138:139], off
	v_lshl_add_u64 v[138:139], s[2:3], 0, v[128:129]
	s_add_i32 m0, s1, 0x2000
	s_nop 0
	global_load_lds_dwordx4 v[138:139], off
	s_waitcnt vmcnt(6)
	s_barrier
	v_mfma_f32_16x16x32_bf16 v[48:51], v[218:221], v[158:161], v[48:51]
	v_mfma_f32_16x16x32_bf16 v[40:43], v[226:229], v[158:161], v[40:43]
	v_mfma_f32_16x16x32_bf16 v[32:35], v[218:221], v[166:169], v[32:35]
	v_mfma_f32_16x16x32_bf16 v[24:27], v[226:229], v[166:169], v[24:27]
	v_mfma_f32_16x16x32_bf16 v[16:19], v[218:221], v[182:185], v[16:19]
	v_mfma_f32_16x16x32_bf16 v[8:11], v[226:229], v[182:185], v[8:11]
	v_mfma_f32_16x16x32_bf16 v[4:7], v[218:221], v[210:213], v[4:7]
	v_mfma_f32_16x16x32_bf16 v[0:3], v[226:229], v[210:213], v[0:3]
	v_mfma_f32_16x16x32_bf16 v[48:51], v[222:225], v[162:165], v[48:51]
	v_mfma_f32_16x16x32_bf16 v[40:43], v[230:233], v[162:165], v[40:43]
	v_mfma_f32_16x16x32_bf16 v[32:35], v[222:225], v[170:173], v[32:35]
	v_mfma_f32_16x16x32_bf16 v[24:27], v[230:233], v[170:173], v[24:27]
	v_mfma_f32_16x16x32_bf16 v[16:19], v[222:225], v[206:209], v[16:19]
	v_mfma_f32_16x16x32_bf16 v[8:11], v[230:233], v[206:209], v[8:11]
	v_mfma_f32_16x16x32_bf16 v[4:7], v[222:225], v[214:217], v[4:7]
	v_mfma_f32_16x16x32_bf16 v[0:3], v[230:233], v[214:217], v[0:3]
	s_add_i32 s87, s87, 2
	s_add_u32 s68, s68, 0x100
	s_addc_u32 s69, s69, 0
	s_add_u32 s83, s83, 0x100
	s_addc_u32 s86, s86, 0
	s_cmp_gt_u32 s87, 29
	s_barrier
	s_cbranch_scc0 .LBB0_189
	s_setprio 0
	s_cmp_eq_u32 s88, 0
	s_cbranch_scc1 .Lrs_skip
	s_add_i32 s98, s80, 1
	s_nop 0
	s_cmp_eq_u32 s89, s98
	s_cbranch_scc1 .Lrs_mul
	v_readlane_b32 s98, v255, 1
	v_readlane_b32 s99, v255, 2
	v_lshl_add_u32 v200, s80, 8, v142
	v_bfe_u32 v201, v144, 3, 2
	v_lshlrev_b32_e32 v201, 5, v201
	v_lshl_add_u32 v200, v200, 7, v201
	v_add_u32_e32 v201, 0x1000, v200
	v_add_u32_e32 v202, 0x4000, v200
	v_add_u32_e32 v203, 0x5000, v200
	v_mbcnt_lo_u32_b32 v204, -1, 0
	v_mbcnt_hi_u32_b32 v204, -1, v204
	v_xor_b32_e32 v205, 16, v204
	v_xor_b32_e32 v204, 32, v204
	v_lshlrev_b32_e32 v205, 2, v205
	v_lshlrev_b32_e32 v204, 2, v204
	global_load_dwordx4 v[208:211], v200, s[98:99]
	global_load_dwordx4 v[212:215], v200, s[98:99] offset:16
	global_load_dwordx4 v[216:219], v200, s[98:99] offset:2048
	global_load_dwordx4 v[220:223], v200, s[98:99] offset:2064
	global_load_dwordx4 v[224:227], v201, s[98:99]
	global_load_dwordx4 v[228:231], v201, s[98:99] offset:16
	global_load_dwordx4 v[232:235], v201, s[98:99] offset:2048
	global_load_dwordx4 v[236:239], v201, s[98:99] offset:2064
	s_waitcnt vmcnt(0)
	v_add_f32_e32 v208, v208, v209
	v_add_f32_e32 v210, v210, v211
	v_add_f32_e32 v212, v212, v213
	v_add_f32_e32 v214, v214, v215
	v_add_f32_e32 v208, v208, v210
	v_add_f32_e32 v212, v212, v214
	v_add_f32_e32 v190, v208, v212
	v_add_f32_e32 v216, v216, v217
	v_add_f32_e32 v218, v218, v219
	v_add_f32_e32 v220, v220, v221
	v_add_f32_e32 v222, v222, v223
	v_add_f32_e32 v216, v216, v218
	v_add_f32_e32 v220, v220, v222
	v_add_f32_e32 v191, v216, v220
	v_add_f32_e32 v224, v224, v225
	v_add_f32_e32 v226, v226, v227
	v_add_f32_e32 v228, v228, v229
	v_add_f32_e32 v230, v230, v231
	v_add_f32_e32 v224, v224, v226
	v_add_f32_e32 v228, v228, v230
	v_add_f32_e32 v192, v224, v228
	v_add_f32_e32 v232, v232, v233
	v_add_f32_e32 v234, v234, v235
	v_add_f32_e32 v236, v236, v237
	v_add_f32_e32 v238, v238, v239
	v_add_f32_e32 v232, v232, v234
	v_add_f32_e32 v236, v236, v238
	v_add_f32_e32 v194, v232, v236
	global_load_dwordx4 v[208:211], v202, s[98:99]
	global_load_dwordx4 v[212:215], v202, s[98:99] offset:16
	global_load_dwordx4 v[216:219], v202, s[98:99] offset:2048
	global_load_dwordx4 v[220:223], v202, s[98:99] offset:2064
	global_load_dwordx4 v[224:227], v203, s[98:99]
	global_load_dwordx4 v[228:231], v203, s[98:99] offset:16
	global_load_dwordx4 v[232:235], v203, s[98:99] offset:2048
	global_load_dwordx4 v[236:239], v203, s[98:99] offset:2064
	s_waitcnt vmcnt(0)
	v_add_f32_e32 v208, v208, v209
	v_add_f32_e32 v210, v210, v211
	v_add_f32_e32 v212, v212, v213
	v_add_f32_e32 v214, v214, v215
	v_add_f32_e32 v208, v208, v210
	v_add_f32_e32 v212, v212, v214
	v_add_f32_e32 v195, v208, v212
	v_add_f32_e32 v216, v216, v217
	v_add_f32_e32 v218, v218, v219
	v_add_f32_e32 v220, v220, v221
	v_add_f32_e32 v222, v222, v223
	v_add_f32_e32 v216, v216, v218
	v_add_f32_e32 v220, v220, v222
	v_add_f32_e32 v196, v216, v220
	v_add_f32_e32 v224, v224, v225
	v_add_f32_e32 v226, v226, v227
	v_add_f32_e32 v228, v228, v229
	v_add_f32_e32 v230, v230, v231
	v_add_f32_e32 v224, v224, v226
	v_add_f32_e32 v228, v228, v230
	v_add_f32_e32 v198, v224, v228
	v_add_f32_e32 v232, v232, v233
	v_add_f32_e32 v234, v234, v235
	v_add_f32_e32 v236, v236, v237
	v_add_f32_e32 v238, v238, v239
	v_add_f32_e32 v232, v232, v234
	v_add_f32_e32 v236, v236, v238
	v_add_f32_e32 v248, v232, v236
	ds_bpermute_b32 v240, v205, v190
	ds_bpermute_b32 v241, v205, v191
	ds_bpermute_b32 v242, v205, v192
	ds_bpermute_b32 v243, v205, v194
	ds_bpermute_b32 v244, v205, v195
	ds_bpermute_b32 v245, v205, v196
	ds_bpermute_b32 v246, v205, v198
	ds_bpermute_b32 v247, v205, v248
	s_waitcnt lgkmcnt(0)
	v_add_f32_e32 v190, v190, v240
	v_add_f32_e32 v191, v191, v241
	v_add_f32_e32 v192, v192, v242
	v_add_f32_e32 v194, v194, v243
	v_add_f32_e32 v195, v195, v244
	v_add_f32_e32 v196, v196, v245
	v_add_f32_e32 v198, v198, v246
	v_add_f32_e32 v248, v248, v247
	ds_bpermute_b32 v240, v204, v190
	ds_bpermute_b32 v241, v204, v191
	ds_bpermute_b32 v242, v204, v192
	ds_bpermute_b32 v243, v204, v194
	ds_bpermute_b32 v244, v204, v195
	ds_bpermute_b32 v245, v204, v196
	ds_bpermute_b32 v246, v204, v198
	ds_bpermute_b32 v247, v204, v248
	s_waitcnt lgkmcnt(0)
	v_add_f32_e32 v190, v190, v240
	v_add_f32_e32 v191, v191, v241
	v_add_f32_e32 v192, v192, v242
	v_add_f32_e32 v194, v194, v243
	v_add_f32_e32 v195, v195, v244
	v_add_f32_e32 v196, v196, v245
	v_add_f32_e32 v198, v198, v246
	v_add_f32_e32 v248, v248, v247
	v_mul_f32_e32 v190, 0x3a000000, v190
	v_add_f32_e32 v190, 0x358637bd, v190
	v_mul_f32_e32 v191, 0x3a000000, v191
	v_add_f32_e32 v191, 0x358637bd, v191
	v_mul_f32_e32 v192, 0x3a000000, v192
	v_add_f32_e32 v192, 0x358637bd, v192
	v_mul_f32_e32 v194, 0x3a000000, v194
	v_add_f32_e32 v194, 0x358637bd, v194
	v_mul_f32_e32 v195, 0x3a000000, v195
	v_add_f32_e32 v195, 0x358637bd, v195
	v_mul_f32_e32 v196, 0x3a000000, v196
	v_add_f32_e32 v196, 0x358637bd, v196
	v_mul_f32_e32 v198, 0x3a000000, v198
	v_add_f32_e32 v198, 0x358637bd, v198
	v_mul_f32_e32 v248, 0x3a000000, v248
	v_add_f32_e32 v248, 0x358637bd, v248
	v_rsq_f32_e32 v190, v190
	v_rsq_f32_e32 v191, v191
	v_rsq_f32_e32 v192, v192
	v_rsq_f32_e32 v194, v194
	v_rsq_f32_e32 v195, v195
	v_rsq_f32_e32 v196, v196
	v_rsq_f32_e32 v198, v198
	v_rsq_f32_e32 v248, v248
	s_add_i32 s89, s80, 1

.Lprio_357:
	s_add_u32 s1, s70, s30
	s_addc_u32 s12, s71, 0
	s_add_u32 s13, s1, 0x100
	s_addc_u32 s14, s12, 0
	s_and_b64 s[2:3], s[74:75], exec
	s_cselect_b32 s79, s43, s14
	s_cselect_b32 s78, s95, s13
	s_add_u32 s2, s68, s30
	s_addc_u32 s3, s69, 0
	s_add_u32 s13, s2, 0x100
	s_addc_u32 s14, s3, 0
	s_add_i32 s15, 0, 0x10000
	s_and_b64 s[2:3], s[74:75], exec
	s_cselect_b32 s81, s39, s14
	s_cselect_b32 s80, s96, s13
	s_add_u32 s82, s1, 0x10080
	s_addc_u32 s83, s12, 0
	s_add_i32 s12, s15, s61
	s_add_i32 m0, s85, 0xc000
	s_add_i32 s86, s85, 0xe000
	s_add_i32 s13, 0, 0x14000
	s_add_i32 s14, s12, 0x2000
	s_add_u32 s76, s80, 0x10000
	v_add_u32_e32 v134, s15, v137
	s_addc_u32 s77, s81, 0
	s_add_i32 s2, s13, s61
	ds_read_b128 v[140:143], v134
	ds_read_b128 v[144:147], v134 offset:1024
	ds_read_b128 v[148:151], v134 offset:2048
	ds_read_b128 v[152:155], v134 offset:3072
	s_add_i32 s3, s2, 0x2000
	s_add_i32 s97, 0, 0x18000
	s_add_u32 vcc_lo, s78, 0x10000
	s_addc_u32 vcc_hi, s79, 0
	s_add_i32 s30, s97, s61
	s_add_i32 s31, 0, 0x1c000
	s_add_i32 s1, s30, 0x2000
	s_add_u32 s74, s80, 0x10080
	s_addc_u32 s75, s81, 0
	s_add_i32 s34, s31, s61
	s_add_i32 s48, s34, 0x2000
	v_lshl_add_u64 v[134:135], s[82:83], 0, v[132:133]
	ds_read_b128 v[156:159], v139
	ds_read_b128 v[160:163], v139 offset:1024
	ds_read_b128 v[164:167], v139 offset:2048
	ds_read_b128 v[168:171], v139 offset:3072
	ds_read_b128 v[172:175], v139 offset:4096
	ds_read_b128 v[182:185], v139 offset:5120
	ds_read_b128 v[200:203], v139 offset:6144
	ds_read_b128 v[206:209], v139 offset:7168
	global_load_lds_dwordx4 v[134:135], off
	v_lshl_add_u64 v[134:135], s[82:83], 0, v[130:131]
	s_mov_b32 m0, s86
	s_nop 0
	global_load_lds_dwordx4 v[134:135], off
	s_waitcnt lgkmcnt(8)
	s_barrier
	s_waitcnt lgkmcnt(0)
	s_waitcnt lgkmcnt(0)
	v_mfma_f32_16x16x32_bf16 v[124:127], v[140:143], v[156:159], v[124:127]
	v_mfma_f32_16x16x32_bf16 v[120:123], v[148:151], v[156:159], v[120:123]
	v_mfma_f32_16x16x32_bf16 v[116:119], v[140:143], v[164:167], v[116:119]
	v_mfma_f32_16x16x32_bf16 v[108:111], v[148:151], v[164:167], v[108:111]
	v_mfma_f32_16x16x32_bf16 v[100:103], v[140:143], v[172:175], v[100:103]
	v_mfma_f32_16x16x32_bf16 v[92:95], v[148:151], v[172:175], v[92:95]
	v_mfma_f32_16x16x32_bf16 v[84:87], v[140:143], v[200:203], v[84:87]
	v_mfma_f32_16x16x32_bf16 v[76:79], v[148:151], v[200:203], v[76:79]
	v_mfma_f32_16x16x32_bf16 v[124:127], v[144:147], v[160:163], v[124:127]
	v_mfma_f32_16x16x32_bf16 v[120:123], v[152:155], v[160:163], v[120:123]
	v_mfma_f32_16x16x32_bf16 v[116:119], v[144:147], v[168:171], v[116:119]
	v_mfma_f32_16x16x32_bf16 v[108:111], v[152:155], v[168:171], v[108:111]
	v_mfma_f32_16x16x32_bf16 v[100:103], v[144:147], v[182:185], v[100:103]
	v_mfma_f32_16x16x32_bf16 v[92:95], v[152:155], v[182:185], v[92:95]
	v_mfma_f32_16x16x32_bf16 v[84:87], v[144:147], v[206:209], v[84:87]
	v_mfma_f32_16x16x32_bf16 v[76:79], v[152:155], v[206:209], v[76:79]
	s_barrier
	v_add_u32_e32 v134, s13, v137
	s_mov_b32 m0, s12
	ds_read_b128 v[210:213], v134
	ds_read_b128 v[214:217], v134 offset:1024
	ds_read_b128 v[218:221], v134 offset:2048
	ds_read_b128 v[222:225], v134 offset:3072
	v_lshl_add_u64 v[134:135], s[80:81], 0, v[176:177]
	global_load_lds_dwordx4 v[134:135], off
	v_lshl_add_u64 v[186:187], s[80:81], 0, v[128:129]
	s_mov_b32 m0, s14
	s_nop 0
	global_load_lds_dwordx4 v[186:187], off
	s_barrier
	s_waitcnt lgkmcnt(0)
	s_waitcnt lgkmcnt(0)
	v_mfma_f32_16x16x32_bf16 v[112:115], v[210:213], v[156:159], v[112:115]
	v_mfma_f32_16x16x32_bf16 v[104:107], v[218:221], v[156:159], v[104:107]
	v_mfma_f32_16x16x32_bf16 v[96:99], v[210:213], v[164:167], v[96:99]
	v_mfma_f32_16x16x32_bf16 v[88:91], v[218:221], v[164:167], v[88:91]
	v_mfma_f32_16x16x32_bf16 v[80:83], v[210:213], v[172:175], v[80:83]
	v_mfma_f32_16x16x32_bf16 v[72:75], v[218:221], v[172:175], v[72:75]
	v_mfma_f32_16x16x32_bf16 v[68:71], v[210:213], v[200:203], v[68:71]
	v_mfma_f32_16x16x32_bf16 v[64:67], v[218:221], v[200:203], v[64:67]
	v_mfma_f32_16x16x32_bf16 v[112:115], v[214:217], v[160:163], v[112:115]
	v_mfma_f32_16x16x32_bf16 v[104:107], v[222:225], v[160:163], v[104:107]
	v_mfma_f32_16x16x32_bf16 v[96:99], v[214:217], v[168:171], v[96:99]
	v_mfma_f32_16x16x32_bf16 v[88:91], v[222:225], v[168:171], v[88:91]
	v_mfma_f32_16x16x32_bf16 v[80:83], v[214:217], v[182:185], v[80:83]
	v_mfma_f32_16x16x32_bf16 v[72:75], v[222:225], v[182:185], v[72:75]
	v_mfma_f32_16x16x32_bf16 v[68:71], v[214:217], v[206:209], v[68:71]
	v_mfma_f32_16x16x32_bf16 v[64:67], v[222:225], v[206:209], v[64:67]
	s_mov_b32 m0, s85
	v_lshl_add_u64 v[190:191], s[78:79], 0, v[132:133]
	s_barrier
	ds_read_b128 v[156:159], v139 offset:16384
	ds_read_b128 v[160:163], v139 offset:17408
	ds_read_b128 v[164:167], v139 offset:18432
	ds_read_b128 v[168:171], v139 offset:19456
	ds_read_b128 v[172:175], v139 offset:20480
	ds_read_b128 v[182:185], v139 offset:21504
	ds_read_b128 v[200:203], v139 offset:22528
	ds_read_b128 v[206:209], v139 offset:23552
	global_load_lds_dwordx4 v[190:191], off
	v_lshl_add_u64 v[194:195], s[78:79], 0, v[130:131]
	s_mov_b32 m0, s87
	s_nop 0
	global_load_lds_dwordx4 v[194:195], off
	s_barrier
	s_waitcnt lgkmcnt(0)
	s_waitcnt lgkmcnt(0)
	v_mfma_f32_16x16x32_bf16 v[60:63], v[140:143], v[156:159], v[60:63]
	v_mfma_f32_16x16x32_bf16 v[56:59], v[148:151], v[156:159], v[56:59]
	v_mfma_f32_16x16x32_bf16 v[52:55], v[140:143], v[164:167], v[52:55]
	v_mfma_f32_16x16x32_bf16 v[44:47], v[148:151], v[164:167], v[44:47]
	v_mfma_f32_16x16x32_bf16 v[36:39], v[140:143], v[172:175], v[36:39]
	v_mfma_f32_16x16x32_bf16 v[28:31], v[148:151], v[172:175], v[28:31]
	v_mfma_f32_16x16x32_bf16 v[20:23], v[140:143], v[200:203], v[20:23]
	v_mfma_f32_16x16x32_bf16 v[12:15], v[148:151], v[200:203], v[12:15]
	v_mfma_f32_16x16x32_bf16 v[60:63], v[144:147], v[160:163], v[60:63]
	v_mfma_f32_16x16x32_bf16 v[56:59], v[152:155], v[160:163], v[56:59]
	v_mfma_f32_16x16x32_bf16 v[52:55], v[144:147], v[168:171], v[52:55]
	v_mfma_f32_16x16x32_bf16 v[44:47], v[152:155], v[168:171], v[44:47]
	v_mfma_f32_16x16x32_bf16 v[36:39], v[144:147], v[182:185], v[36:39]
	v_mfma_f32_16x16x32_bf16 v[28:31], v[152:155], v[182:185], v[28:31]
	v_mfma_f32_16x16x32_bf16 v[20:23], v[144:147], v[206:209], v[20:23]
	v_mfma_f32_16x16x32_bf16 v[12:15], v[152:155], v[206:209], v[12:15]
	s_barrier
	s_mov_b32 m0, s2
	v_lshl_add_u64 v[140:141], s[76:77], 0, v[176:177]
	global_load_lds_dwordx4 v[140:141], off
	v_lshl_add_u64 v[140:141], s[76:77], 0, v[128:129]
	s_mov_b32 m0, s3
	s_nop 0
	global_load_lds_dwordx4 v[140:141], off
	s_waitcnt vmcnt(6)
	s_barrier
	v_mfma_f32_16x16x32_bf16 v[48:51], v[210:213], v[156:159], v[48:51]
	v_mfma_f32_16x16x32_bf16 v[40:43], v[218:221], v[156:159], v[40:43]
	v_mfma_f32_16x16x32_bf16 v[32:35], v[210:213], v[164:167], v[32:35]
	v_mfma_f32_16x16x32_bf16 v[24:27], v[218:221], v[164:167], v[24:27]
	v_mfma_f32_16x16x32_bf16 v[16:19], v[210:213], v[172:175], v[16:19]
	v_mfma_f32_16x16x32_bf16 v[8:11], v[218:221], v[172:175], v[8:11]
	v_mfma_f32_16x16x32_bf16 v[4:7], v[210:213], v[200:203], v[4:7]
	v_mfma_f32_16x16x32_bf16 v[0:3], v[218:221], v[200:203], v[0:3]
	v_mfma_f32_16x16x32_bf16 v[48:51], v[214:217], v[160:163], v[48:51]
	v_mfma_f32_16x16x32_bf16 v[40:43], v[222:225], v[160:163], v[40:43]
	v_mfma_f32_16x16x32_bf16 v[32:35], v[214:217], v[168:171], v[32:35]
	v_mfma_f32_16x16x32_bf16 v[24:27], v[222:225], v[168:171], v[24:27]
	v_mfma_f32_16x16x32_bf16 v[16:19], v[214:217], v[182:185], v[16:19]
	v_mfma_f32_16x16x32_bf16 v[8:11], v[222:225], v[182:185], v[8:11]
	v_mfma_f32_16x16x32_bf16 v[4:7], v[214:217], v[206:209], v[4:7]
	v_mfma_f32_16x16x32_bf16 v[0:3], v[222:225], v[206:209], v[0:3]
	v_add_u32_e32 v152, s97, v137
	s_barrier
	ds_read_b128 v[140:143], v152
	ds_read_b128 v[144:147], v152 offset:1024
	ds_read_b128 v[148:151], v152 offset:2048
	ds_read_b128 v[152:155], v152 offset:3072
	s_mov_b32 m0, s88
	v_lshl_add_u64 v[204:205], vcc, 0, v[132:133]
	ds_read_b128 v[156:159], v139 offset:32768
	ds_read_b128 v[160:163], v139 offset:33792
	ds_read_b128 v[164:167], v139 offset:34816
	ds_read_b128 v[168:171], v139 offset:35840
	ds_read_b128 v[172:175], v139 offset:36864
	ds_read_b128 v[182:185], v139 offset:37888
	ds_read_b128 v[200:203], v139 offset:38912
	ds_read_b128 v[206:209], v139 offset:39936
	global_load_lds_dwordx4 v[204:205], off
	v_lshl_add_u64 v[204:205], vcc, 0, v[130:131]
	s_mov_b32 m0, s89
	s_nop 0
	global_load_lds_dwordx4 v[204:205], off
	s_waitcnt lgkmcnt(8)
	s_barrier
	s_waitcnt lgkmcnt(0)
	s_waitcnt lgkmcnt(0)
	v_mfma_f32_16x16x32_bf16 v[124:127], v[140:143], v[156:159], v[124:127]
	v_mfma_f32_16x16x32_bf16 v[120:123], v[148:151], v[156:159], v[120:123]
	v_mfma_f32_16x16x32_bf16 v[116:119], v[140:143], v[164:167], v[116:119]
	v_mfma_f32_16x16x32_bf16 v[108:111], v[148:151], v[164:167], v[108:111]
	v_mfma_f32_16x16x32_bf16 v[100:103], v[140:143], v[172:175], v[100:103]
	v_mfma_f32_16x16x32_bf16 v[92:95], v[148:151], v[172:175], v[92:95]
	v_mfma_f32_16x16x32_bf16 v[84:87], v[140:143], v[200:203], v[84:87]
	v_mfma_f32_16x16x32_bf16 v[76:79], v[148:151], v[200:203], v[76:79]
	v_mfma_f32_16x16x32_bf16 v[124:127], v[144:147], v[160:163], v[124:127]
	v_mfma_f32_16x16x32_bf16 v[120:123], v[152:155], v[160:163], v[120:123]
	v_mfma_f32_16x16x32_bf16 v[116:119], v[144:147], v[168:171], v[116:119]
	v_mfma_f32_16x16x32_bf16 v[108:111], v[152:155], v[168:171], v[108:111]
	v_mfma_f32_16x16x32_bf16 v[100:103], v[144:147], v[182:185], v[100:103]
	v_mfma_f32_16x16x32_bf16 v[92:95], v[152:155], v[182:185], v[92:95]
	v_mfma_f32_16x16x32_bf16 v[84:87], v[144:147], v[206:209], v[84:87]
	v_mfma_f32_16x16x32_bf16 v[76:79], v[152:155], v[206:209], v[76:79]
	s_barrier
	s_mov_b32 m0, s30
	v_add_u32_e32 v188, s31, v137
	v_lshl_add_u64 v[134:135], v[134:135], 0, s[20:21]
	ds_read_b128 v[210:213], v188
	ds_read_b128 v[214:217], v188 offset:1024
	ds_read_b128 v[218:221], v188 offset:2048
	ds_read_b128 v[222:225], v188 offset:3072
	global_load_lds_dwordx4 v[134:135], off
	v_lshl_add_u64 v[134:135], v[186:187], 0, s[20:21]
	s_mov_b32 m0, s1
	s_nop 0
	global_load_lds_dwordx4 v[134:135], off
	s_barrier
	s_waitcnt lgkmcnt(0)
	s_waitcnt lgkmcnt(0)
	v_mfma_f32_16x16x32_bf16 v[112:115], v[210:213], v[156:159], v[112:115]
	v_mfma_f32_16x16x32_bf16 v[104:107], v[218:221], v[156:159], v[104:107]
	v_mfma_f32_16x16x32_bf16 v[96:99], v[210:213], v[164:167], v[96:99]
	v_mfma_f32_16x16x32_bf16 v[88:91], v[218:221], v[164:167], v[88:91]
	v_mfma_f32_16x16x32_bf16 v[80:83], v[210:213], v[172:175], v[80:83]
	v_mfma_f32_16x16x32_bf16 v[72:75], v[218:221], v[172:175], v[72:75]
	v_mfma_f32_16x16x32_bf16 v[68:71], v[210:213], v[200:203], v[68:71]
	v_mfma_f32_16x16x32_bf16 v[64:67], v[218:221], v[200:203], v[64:67]
	v_mfma_f32_16x16x32_bf16 v[112:115], v[214:217], v[160:163], v[112:115]
	v_mfma_f32_16x16x32_bf16 v[104:107], v[222:225], v[160:163], v[104:107]
	v_mfma_f32_16x16x32_bf16 v[96:99], v[214:217], v[168:171], v[96:99]
	v_mfma_f32_16x16x32_bf16 v[88:91], v[222:225], v[168:171], v[88:91]
	v_mfma_f32_16x16x32_bf16 v[80:83], v[214:217], v[182:185], v[80:83]
	v_mfma_f32_16x16x32_bf16 v[72:75], v[222:225], v[182:185], v[72:75]
	v_mfma_f32_16x16x32_bf16 v[68:71], v[214:217], v[206:209], v[68:71]
	v_mfma_f32_16x16x32_bf16 v[64:67], v[222:225], v[206:209], v[64:67]
	s_mov_b32 m0, s90
	v_lshl_add_u64 v[134:135], v[190:191], 0, s[20:21]
	s_barrier
	ds_read_b128 v[156:159], v139 offset:49152
	ds_read_b128 v[160:163], v139 offset:50176
	ds_read_b128 v[164:167], v139 offset:51200
	ds_read_b128 v[168:171], v139 offset:52224
	ds_read_b128 v[172:175], v139 offset:53248
	ds_read_b128 v[182:185], v139 offset:54272
	ds_read_b128 v[200:203], v139 offset:55296
	ds_read_b128 v[206:209], v139 offset:56320
	global_load_lds_dwordx4 v[134:135], off
	v_lshl_add_u64 v[134:135], v[194:195], 0, s[20:21]
	s_mov_b32 m0, s91
	s_nop 0
	global_load_lds_dwordx4 v[134:135], off
	s_barrier
	s_waitcnt lgkmcnt(0)
	s_waitcnt lgkmcnt(0)
	v_mfma_f32_16x16x32_bf16 v[60:63], v[140:143], v[156:159], v[60:63]
	v_mfma_f32_16x16x32_bf16 v[56:59], v[148:151], v[156:159], v[56:59]
	v_mfma_f32_16x16x32_bf16 v[52:55], v[140:143], v[164:167], v[52:55]
	v_mfma_f32_16x16x32_bf16 v[44:47], v[148:151], v[164:167], v[44:47]
	v_mfma_f32_16x16x32_bf16 v[36:39], v[140:143], v[172:175], v[36:39]
	v_mfma_f32_16x16x32_bf16 v[28:31], v[148:151], v[172:175], v[28:31]
	v_mfma_f32_16x16x32_bf16 v[20:23], v[140:143], v[200:203], v[20:23]
	v_mfma_f32_16x16x32_bf16 v[12:15], v[148:151], v[200:203], v[12:15]
	v_mfma_f32_16x16x32_bf16 v[60:63], v[144:147], v[160:163], v[60:63]
	v_mfma_f32_16x16x32_bf16 v[56:59], v[152:155], v[160:163], v[56:59]
	v_mfma_f32_16x16x32_bf16 v[52:55], v[144:147], v[168:171], v[52:55]
	v_mfma_f32_16x16x32_bf16 v[44:47], v[152:155], v[168:171], v[44:47]
	v_mfma_f32_16x16x32_bf16 v[36:39], v[144:147], v[182:185], v[36:39]
	v_mfma_f32_16x16x32_bf16 v[28:31], v[152:155], v[182:185], v[28:31]
	v_mfma_f32_16x16x32_bf16 v[20:23], v[144:147], v[206:209], v[20:23]
	v_mfma_f32_16x16x32_bf16 v[12:15], v[152:155], v[206:209], v[12:15]
	s_barrier
	s_mov_b32 m0, s34
	v_lshl_add_u64 v[134:135], s[74:75], 0, v[176:177]
	global_load_lds_dwordx4 v[134:135], off
	v_lshl_add_u64 v[134:135], s[74:75], 0, v[128:129]
	s_mov_b32 m0, s48
	s_nop 0
	global_load_lds_dwordx4 v[134:135], off
	s_waitcnt vmcnt(6)
	s_barrier
	v_mfma_f32_16x16x32_bf16 v[48:51], v[210:213], v[156:159], v[48:51]
	v_mfma_f32_16x16x32_bf16 v[40:43], v[218:221], v[156:159], v[40:43]
	v_mfma_f32_16x16x32_bf16 v[32:35], v[210:213], v[164:167], v[32:35]
	v_mfma_f32_16x16x32_bf16 v[24:27], v[218:221], v[164:167], v[24:27]
	v_mfma_f32_16x16x32_bf16 v[16:19], v[210:213], v[172:175], v[16:19]
	v_mfma_f32_16x16x32_bf16 v[8:11], v[218:221], v[172:175], v[8:11]
	v_mfma_f32_16x16x32_bf16 v[4:7], v[210:213], v[200:203], v[4:7]
	v_mfma_f32_16x16x32_bf16 v[0:3], v[218:221], v[200:203], v[0:3]
	v_mfma_f32_16x16x32_bf16 v[48:51], v[214:217], v[160:163], v[48:51]
	v_mfma_f32_16x16x32_bf16 v[40:43], v[222:225], v[160:163], v[40:43]
	v_mfma_f32_16x16x32_bf16 v[32:35], v[214:217], v[168:171], v[32:35]
	v_mfma_f32_16x16x32_bf16 v[24:27], v[222:225], v[168:171], v[24:27]
	v_mfma_f32_16x16x32_bf16 v[16:19], v[214:217], v[182:185], v[16:19]
	v_mfma_f32_16x16x32_bf16 v[8:11], v[222:225], v[182:185], v[8:11]
	v_mfma_f32_16x16x32_bf16 v[4:7], v[214:217], v[206:209], v[4:7]
	v_mfma_f32_16x16x32_bf16 v[0:3], v[222:225], v[206:209], v[0:3]
	s_movk_i32 s30, 0x100
	s_andn2_b64 vcc, exec, s[72:73]
	s_mov_b64 s[74:75], -1
	s_mov_b64 s[72:73], 0
	s_barrier
	s_cbranch_vccz .LBB0_357
	s_setprio 0
	s_nop 0
	v_lshl_add_u32 v140, s94, 8, v136
	v_lshl_or_b32 v134, s93, 8, v138
	v_ashrrev_i32_e32 v141, 31, v140
	v_ashrrev_i32_e32 v135, 31, v134
	v_lshlrev_b64 v[142:143], 12, v[140:141]
	v_lshl_add_u64 v[142:143], s[56:57], 0, v[142:143]
	v_lshlrev_b64 v[144:145], 1, v[134:135]
	v_lshl_add_u64 v[134:135], v[142:143], 0, v[144:145]
	v_cvt_pk_bf16_f32 v124, v124, v125
	v_cvt_pk_bf16_f32 v125, v126, v127
	v_cvt_pk_bf16_f32 v126, v120, v121
	v_cvt_pk_bf16_f32 v127, v122, v123
	global_store_dwordx4 v[134:135], v[124:127], off
	v_cvt_pk_bf16_f32 v112, v112, v113
	v_cvt_pk_bf16_f32 v113, v114, v115
	v_cvt_pk_bf16_f32 v114, v104, v105
	v_or_b32_e32 v104, 16, v140
	v_ashrrev_i32_e32 v105, 31, v104
	v_lshlrev_b64 v[104:105], 12, v[104:105]
	v_lshl_add_u64 v[104:105], s[56:57], 0, v[104:105]
	v_cvt_pk_bf16_f32 v115, v106, v107
	global_store_dwordx4 v[134:135], v[112:115], off offset:256
	s_mov_b32 s1, 0x80000
	s_mov_b64 s[2:3], 0x90000
	v_lshl_add_u64 v[112:113], v[104:105], 0, v[144:145]
	v_cvt_pk_bf16_f32 v104, v116, v117
	v_cvt_pk_bf16_f32 v105, v118, v119
	v_cvt_pk_bf16_f32 v106, v108, v109
	v_cvt_pk_bf16_f32 v107, v110, v111
	global_store_dwordx4 v[112:113], v[104:107], off
	v_cvt_pk_bf16_f32 v96, v96, v97
	v_cvt_pk_bf16_f32 v97, v98, v99
	v_cvt_pk_bf16_f32 v98, v88, v89
	v_or_b32_e32 v88, 32, v140
	v_ashrrev_i32_e32 v89, 31, v88
	v_lshlrev_b64 v[88:89], 12, v[88:89]
	v_lshl_add_u64 v[88:89], s[56:57], 0, v[88:89]
	v_cvt_pk_bf16_f32 v99, v90, v91
	global_store_dwordx4 v[112:113], v[96:99], off offset:256
	v_readlane_b32 s30, v255, 27
	s_mov_b32 s93, s38
	v_lshl_add_u64 v[96:97], v[88:89], 0, v[144:145]
	v_cvt_pk_bf16_f32 v88, v100, v101
	v_cvt_pk_bf16_f32 v89, v102, v103
	v_cvt_pk_bf16_f32 v90, v92, v93
	v_cvt_pk_bf16_f32 v91, v94, v95
	global_store_dwordx4 v[96:97], v[88:91], off
	v_cvt_pk_bf16_f32 v80, v80, v81
	v_cvt_pk_bf16_f32 v81, v82, v83
	v_cvt_pk_bf16_f32 v82, v72, v73
	v_or_b32_e32 v72, 48, v140
	v_ashrrev_i32_e32 v73, 31, v72
	v_lshlrev_b64 v[72:73], 12, v[72:73]
	v_lshl_add_u64 v[72:73], s[56:57], 0, v[72:73]
	v_cvt_pk_bf16_f32 v83, v74, v75
	global_store_dwordx4 v[96:97], v[80:83], off offset:256
	s_mov_b32 s94, s42
	s_mov_b64 s[68:69], s[46:47]
	v_lshl_add_u64 v[80:81], v[72:73], 0, v[144:145]
	v_cvt_pk_bf16_f32 v72, v84, v85
	v_cvt_pk_bf16_f32 v73, v86, v87
	v_cvt_pk_bf16_f32 v74, v76, v77
	v_cvt_pk_bf16_f32 v75, v78, v79
	global_store_dwordx4 v[80:81], v[72:75], off
	v_cvt_pk_bf16_f32 v68, v68, v69
	v_cvt_pk_bf16_f32 v69, v70, v71
	v_cvt_pk_bf16_f32 v70, v64, v65
	v_cvt_pk_bf16_f32 v71, v66, v67
	global_store_dwordx4 v[80:81], v[68:71], off offset:256
	v_cvt_pk_bf16_f32 v60, v60, v61
	v_cvt_pk_bf16_f32 v61, v62, v63
	v_cvt_pk_bf16_f32 v62, v56, v57
	v_add_co_u32_e32 v56, vcc, s1, v134
	v_lshl_add_u64 v[64:65], v[134:135], 0, s[36:37]
	s_nop 0
	v_addc_co_u32_e32 v57, vcc, 0, v135, vcc
	s_mov_b32 s1, 0x90000
	v_cvt_pk_bf16_f32 v63, v58, v59
	global_store_dwordx4 v[56:57], v[60:63], off
	v_cvt_pk_bf16_f32 v48, v48, v49
	v_cvt_pk_bf16_f32 v49, v50, v51
	v_cvt_pk_bf16_f32 v50, v40, v41
	v_cvt_pk_bf16_f32 v51, v42, v43
	global_store_dwordx4 v[64:65], v[48:51], off offset:256
	v_cvt_pk_bf16_f32 v40, v52, v53
	v_cvt_pk_bf16_f32 v41, v54, v55
	v_cvt_pk_bf16_f32 v42, v44, v45
	v_add_co_u32_e32 v44, vcc, s1, v134
	s_nop 0
	v_lshl_add_u64 v[48:49], v[134:135], 0, s[2:3]
	v_addc_co_u32_e32 v45, vcc, 0, v135, vcc
	s_mov_b32 s1, 0xa0000
	v_cvt_pk_bf16_f32 v43, v46, v47
	global_store_dwordx4 v[44:45], v[40:43], off
	v_cvt_pk_bf16_f32 v32, v32, v33
	v_cvt_pk_bf16_f32 v33, v34, v35
	v_cvt_pk_bf16_f32 v34, v24, v25
	v_cvt_pk_bf16_f32 v35, v26, v27
	global_store_dwordx4 v[48:49], v[32:35], off offset:256
	s_mov_b64 s[2:3], 0xa0000
	v_cvt_pk_bf16_f32 v24, v36, v37
	v_cvt_pk_bf16_f32 v25, v38, v39
	v_cvt_pk_bf16_f32 v26, v28, v29
	v_add_co_u32_e32 v28, vcc, s1, v134
	v_lshl_add_u64 v[32:33], v[134:135], 0, s[2:3]
	s_nop 0
	v_addc_co_u32_e32 v29, vcc, 0, v135, vcc
	s_mov_b32 s1, 0xb0000
	v_cvt_pk_bf16_f32 v27, v30, v31
	global_store_dwordx4 v[28:29], v[24:27], off
	v_cvt_pk_bf16_f32 v16, v16, v17
	v_cvt_pk_bf16_f32 v17, v18, v19
	v_cvt_pk_bf16_f32 v18, v8, v9
	v_cvt_pk_bf16_f32 v19, v10, v11
	global_store_dwordx4 v[32:33], v[16:19], off offset:256
	v_cvt_pk_bf16_f32 v8, v20, v21
	v_cvt_pk_bf16_f32 v9, v22, v23
	v_cvt_pk_bf16_f32 v10, v12, v13
	v_add_co_u32_e32 v12, vcc, s1, v134
	s_mov_b64 s[2:3], 0xb0000
	s_nop 0
	v_addc_co_u32_e32 v13, vcc, 0, v135, vcc
	v_lshl_add_u64 v[16:17], v[134:135], 0, s[2:3]
	s_and_b64 vcc, exec, s[40:41]
	s_mov_b64 s[70:71], s[44:45]
	v_readlane_b32 s96, v255, 17
	v_readlane_b32 s31, v255, 28
	v_cvt_pk_bf16_f32 v11, v14, v15
	global_store_dwordx4 v[12:13], v[8:11], off
	v_cvt_pk_bf16_f32 v4, v4, v5
	v_cvt_pk_bf16_f32 v5, v6, v7
	v_cvt_pk_bf16_f32 v6, v0, v1
	v_cvt_pk_bf16_f32 v7, v2, v3
	global_store_dwordx4 v[16:17], v[4:7], off offset:256
	v_readlane_b32 s97, v255, 18
	s_cbranch_vccz .LBB0_350
	s_waitcnt vmcnt(0)
	v_readlane_b32 s1, v255, 36
	v_readlane_b32 s90, v255, 23
	s_cmpk_gt_u32 s1, 0xff
	v_readlane_b32 s48, v255, 21
	v_readlane_b32 s91, v255, 24
	v_readlane_b32 s49, v255, 22
	s_cbranch_scc1 .LBB0_361
	s_barrier
